# N2 step: softmax reference folded into QK accumulator init; lazy reference update (fast path exp2(S') without row-max/rescale when no score exceeds reference by >4 log2 units, original update otherwis
# speedup vs baseline: 1.0256x; 1.0124x over previous
; __device__ void phaseN2_task(const Params& p, int task, char* lds, bf16_t* ydst, int ystride, volatile unsigned* uex, char* ldsb) {
;     ...
;     {
;         const int lo = (t0 & ~31) - 511;
;         const int jb0 = lo > 0 ? (lo >> 6) : 0;
;         const int kkey = t512 >> 3, kch = (t512 & 7) * 8;
;         const int vd = t512 >> 3, vch = (t512 & 7) * 8;
;         const bf16_t* vtb = (const bf16_t*)(p.ws + OFF_VT) + ((size_t)(b * 2 + g) * 64 + vd) * SEQ + vch;
;         u32x4 kreg, vreg;
;         int br = 0, j = 0;
;         {
;             const bf16_t* kb = Z + (rowb + 0) * ZC + ZKS + g * 64;
;             kreg = *(const u32x4*)(kb + (size_t)kkey * ZC + kch);
;             vreg = *(const u32x4*)(vtb);
;         }
;         f32x4 O[2][4];
;         float m[2] = {-1e30f, -1e30f}, l[2] = {0.f, 0.f};
; #pragma unroll
;         for (int x = 0; x < 2; x++)
; #pragma unroll
;             for (int dt = 0; dt < 4; dt++) O[x][dt] = (f32x4){0.f, 0.f, 0.f, 0.f};
.LBB0_616:
	s_or_b64 exec, exec, s[4:5]
	s_lshl_b32 s4, 2, s76
	s_add_i32 s4, s4, -1
	s_cmp_lg_u32 s76, 31
	s_cselect_b32 s10, s4, -2
	s_add_i32 s4, s1, 0xfffffe01
	s_ashr_i32 s11, s4, 6
	s_lshl_b32 s0, s0, 18
	s_add_u32 s4, s92, s0
	v_ashrrev_i32_e32 v49, 31, v48
	s_addc_u32 s5, s93, 0
	s_mul_i32 s0, s88, 0x2700
	v_lshlrev_b64 v[16:17], 12, v[48:49]
	s_add_u32 s0, s90, s0
	v_lshlrev_b32_e32 v25, 3, v124
	v_lshl_add_u64 v[16:17], s[4:5], 0, v[16:17]
	s_addc_u32 s5, s91, 0
	s_lshl_b32 s12, s89, 6
	s_lshl_b32 s4, s89, 7
	v_and_b32_e32 v34, 56, v25
	s_add_u32 s4, s0, s4
	s_movk_i32 s0, 0x1380
	v_lshlrev_b32_e32 v88, 1, v34
	s_addc_u32 s5, s5, 0
	v_mad_i64_i32 v[94:95], s[6:7], v48, s0, 0
	v_lshl_add_u64 v[36:37], v[16:17], 0, v[88:89]
	v_lshl_add_u64 v[16:17], v[94:95], 1, s[4:5]
	v_lshl_add_u64 v[16:17], v[16:17], 0, v[88:89]
	s_movk_i32 s0, 0x2000
	v_add_co_u32_e32 v16, vcc, s0, v16
	s_mov_b32 s0, 0xf800000
	s_nop 0
	v_addc_co_u32_e32 v17, vcc, 0, v17, vcc
	v_mov_b32_e32 v93, v91
	v_add_co_u32_e32 v20, vcc, s0, v36
	s_waitcnt lgkmcnt(0)
	s_barrier
	flat_load_dword v33, v[90:91] sc0 sc1
	s_waitcnt vmcnt(0)
	flat_load_dword v35, v[92:93] sc0 sc1
	s_waitcnt vmcnt(0)
	v_addc_co_u32_e32 v21, vcc, 0, v37, vcc
	global_load_dwordx4 v[16:19], v[16:17], off offset:512
	s_nop 0
	global_load_dwordx4 v[20:23], v[20:21], off
	v_and_b32_e32 v26, 7, v124
	v_lshlrev_b32_e32 v38, 7, v48
	v_bitop3_b32 v27, v75, v124, 7 bitop3:0x78
	v_bitop3_b32 v40, v25, 56, v124 bitop3:0x48
	v_bitop3_b32 v42, v75, v26, 4 bitop3:0x36
	v_lshlrev_b32_e32 v39, 4, v48
	v_lshlrev_b32_e32 v28, 4, v74
	v_lshlrev_b32_e32 v29, 1, v129
	v_mov_b32_e32 v24, 0
	v_lshlrev_b32_e32 v41, 4, v27
	v_lshl_or_b32 v136, v40, 1, v38
	v_lshlrev_b32_e32 v40, 4, v42
	s_mov_b64 s[4:5], 0xf800000
	s_cmpk_gt_i32 s1, 0x1ff
	s_mov_b32 s89, s85
	v_lshrrev_b32_e32 v93, 16, v127
	v_lshrrev_b32_e32 v133, 16, v128
	v_add_u32_e32 v134, 0xfffffe01, v126
	v_mov_b32_e32 v143, 0
	v_mov_b32_e32 v102, 0xf149f2ca
	s_mov_b64 s[8:9], 0
	v_mov_b32_e32 v103, 0xf149f2ca
	v_mov_b32_e32 v56, 0
	v_add3_u32 v135, v51, v28, v29
	v_mov_b32_e32 v25, v24
	v_mov_b32_e32 v26, v24
	v_mov_b32_e32 v27, v24
	v_mov_b32_e32 v28, v24
	v_mov_b32_e32 v29, v24
	v_mov_b32_e32 v30, v24
	v_mov_b32_e32 v31, v24
	v_mov_b32_e32 v32, v24
	v_lshlrev_b32_e32 v96, 1, v34
	v_add_u32_e32 v137, v51, v41
	v_add3_u32 v138, v38, v39, v88
	v_add_u32_e32 v139, v51, v40
	v_lshl_add_u64 v[98:99], v[36:37], 0, s[4:5]
	s_cselect_b32 s0, s11, 0
	s_lshl_b32 s84, s12, 1
	v_mov_b32_e32 v34, v24
	v_mov_b32_e32 v36, v24
	v_mov_b32_e32 v37, v24
	v_mov_b32_e32 v38, v24
	v_mov_b32_e32 v39, v24
	v_mov_b32_e32 v40, v24
	v_mov_b32_e32 v41, v24
	v_mov_b32_e32 v42, v24
	v_mov_b32_e32 v43, v24
	v_mov_b32_e32 v44, v24
	v_mov_b32_e32 v45, v24
	v_mov_b32_e32 v46, v24
	v_mov_b32_e32 v47, v24
	v_mov_b32_e32 v48, v24
	v_mov_b32_e32 v49, v24
	v_mov_b32_e32 v50, v24
	v_mov_b32_e32 v51, v24
	v_mov_b32_e32 v52, v24
	v_mov_b32_e32 v53, v24
	v_mov_b32_e32 v54, v24
	v_mov_b32_e32 v55, v24
	v_mov_b32_e32 v100, v24
	v_mov_b32_e32 v101, v24
	s_waitcnt lgkmcnt(0)
	v_bitop3_b32 v140, v35, s10, v33 bitop3:0xc8
	v_mov_b32_e32 v33, v24
	v_mov_b32_e32 v35, v24
	v_mov_b32_e32 v176, 0
	v_mov_b32_e32 v177, 0
	v_mov_b32_e32 v178, v123
	v_mov_b32_e32 v179, v123
	s_branch .LBB0_618

; __device__ __forceinline__ f32x4 mfma16(bf16x8 a, bf16x8 b, f32x4 c) { return __builtin_amdgcn_mfma_f32_16x16x32_bf16(a, b, c, 0, 0, 0); }
; __device__ __forceinline__ void nsa_block_step(const bf16_t* Ks, const bf16_t* VT, const bf16x8 (&qf)[2][2], f32x4 (&O)[2][4], float (&m)[2], float (&l)[2],
;                                                int klo, int khi, int r, int q) {
;     f32x4 s[2][4];
; #pragma unroll
;     for (int x = 0; x < 2; x++)
; #pragma unroll
;         for (int kt = 0; kt < 4; kt++) s[x][kt] = (f32x4){0.f, 0.f, 0.f, 0.f};
; #pragma unroll
;     for (int kt = 0; kt < 4; kt++)
; #pragma unroll
;         for (int ks = 0; ks < 2; ks++) {
;             const bf16x8 kf = ld_frag(Ks + (kt * 16 + r) * 64 + (((ks * 4 + q) ^ (r & 7)) * 8));
; #pragma unroll
;             for (int x = 0; x < 2; x++) s[x][kt] = mfma16(kf, qf[x][ks], s[x][kt]);
;         }
;     if (!__all((klo <= 0) && (khi >= 63))) {
;         const int a = 4 * q - klo;
;         const unsigned range = (unsigned)(khi - klo);
;         const bool any = khi >= klo;
; #pragma unroll
;         for (int kt = 0; kt < 4; kt++)
; #pragma unroll
;             for (int j = 0; j < 4; j++) {
;                 const bool valid = any && ((unsigned)(kt * 16 + j + a) <= range);
; #pragma unroll
;                 for (int x = 0; x < 2; x++) s[x][kt][j] = valid ? s[x][kt][j] : -3.0e38f;
;             }
;     }
; __device__ void phaseN2_task(const Params& p, int task, char* lds, bf16_t* ydst, int ystride, volatile unsigned* uex, char* ldsb) {
;     ...
;             int klo = 0, khi = -1;
;             if (br == 0) { if ((mysel >> j) & 1u) khi = t - j * 64; }
;             else { khi = t - j * 64; klo = t - 511 - j * 64; }
;             klo = klo < 0 ? 0 : klo;
;             khi = khi > 63 ? 63 : khi;
;             nsa_block_step(Ks, VT, qf, O, m, l, klo, khi, r, q);
.LBB0_622:
	s_or_b64 exec, exec, s[10:11]
	v_lshlrev_b32_e32 v57, 6, v56
	v_sub_u32_e32 v88, v126, v57
	s_and_saveexec_b64 s[6:7], vcc
	s_xor_b64 s[6:7], exec, s[6:7]
	v_sub_u32_e32 v56, v134, v57
	v_max_i32_e32 v97, 0, v56
	s_andn2_saveexec_b64 s[6:7], s[6:7]
	v_lshrrev_b32_e32 v56, v56, v132
	v_and_b32_e32 v56, 1, v56
	v_cmp_eq_u32_e32 vcc, 1, v56
	v_mov_b32_e32 v97, 0
	s_nop 0
	v_cndmask_b32_e32 v88, -1, v88, vcc
	s_or_b64 exec, exec, s[6:7]
	v_cmp_eq_u32_e32 vcc, 0, v97
	v_cmp_lt_i32_e64 s[6:7], 62, v88
	v_cmp_lt_i32_e64 s[48:49], v88, v97
	ds_read_b128 v[56:59], v137
	ds_read_b128 v[60:63], v137 offset:2048
	s_and_b64 s[6:7], vcc, s[6:7]
	s_or_b64 s[46:47], s[6:7], s[48:49]
	s_cmp_eq_u64 s[46:47], exec
	s_cselect_b64 s[48:49], s[48:49], 0
	v_cndmask_b32_e64 v168, v176, v123, s[48:49]
	v_cndmask_b32_e64 v169, v176, v123, s[48:49]
	v_cndmask_b32_e64 v170, v176, v123, s[48:49]
	v_cndmask_b32_e64 v171, v176, v123, s[48:49]
	v_cndmask_b32_e64 v172, v177, v123, s[48:49]
	v_cndmask_b32_e64 v173, v177, v123, s[48:49]
	v_cndmask_b32_e64 v174, v177, v123, s[48:49]
	v_cndmask_b32_e64 v175, v177, v123, s[48:49]
	ds_read_b128 v[68:71], v139
	ds_read_b128 v[76:79], v139 offset:2048
	s_waitcnt lgkmcnt(3)
	v_mfma_f32_16x16x32_bf16 v[64:67], v[56:59], v[0:3], v[168:171]
	v_mfma_f32_16x16x32_bf16 v[56:59], v[56:59], v[8:11], v[172:175]
	s_waitcnt lgkmcnt(1)
	v_mfma_f32_16x16x32_bf16 v[80:83], v[68:71], v[4:7], v[64:67]
	v_mfma_f32_16x16x32_bf16 v[68:71], v[68:71], v[12:15], v[56:59]
	v_mfma_f32_16x16x32_bf16 v[56:59], v[60:63], v[0:3], v[168:171]
	v_mfma_f32_16x16x32_bf16 v[60:63], v[60:63], v[8:11], v[172:175]
	s_waitcnt lgkmcnt(0)
	v_mfma_f32_16x16x32_bf16 v[72:75], v[76:79], v[4:7], v[56:59]
	v_mfma_f32_16x16x32_bf16 v[64:67], v[76:79], v[12:15], v[60:63]
	s_nop 3
	ds_read_b128 v[56:59], v137 offset:4096
	ds_read_b128 v[76:79], v137 offset:6144
	ds_read_b128 v[104:107], v139 offset:4096
	ds_read_b128 v[108:111], v139 offset:6144
	s_waitcnt lgkmcnt(3)
	v_mfma_f32_16x16x32_bf16 v[60:63], v[56:59], v[0:3], v[168:171]
	v_mfma_f32_16x16x32_bf16 v[56:59], v[56:59], v[8:11], v[172:175]
	s_waitcnt lgkmcnt(1)
	v_mfma_f32_16x16x32_bf16 v[84:87], v[104:107], v[4:7], v[60:63]
	v_mfma_f32_16x16x32_bf16 v[60:63], v[104:107], v[12:15], v[56:59]
	v_mfma_f32_16x16x32_bf16 v[56:59], v[76:79], v[0:3], v[168:171]
	v_mfma_f32_16x16x32_bf16 v[104:107], v[76:79], v[8:11], v[172:175]
	s_waitcnt lgkmcnt(0)
	v_mfma_f32_16x16x32_bf16 v[76:79], v[108:111], v[4:7], v[56:59]
	v_mfma_f32_16x16x32_bf16 v[56:59], v[108:111], v[12:15], v[104:107]
	s_cmp_eq_u64 s[46:47], exec
	s_cbranch_scc1 .LBB0_628
	v_min_i32_e32 v88, 63, v88
	v_sub_u32_e32 v104, v88, v97
	v_cmp_ge_i32_e32 vcc, v88, v97
	v_sub_u32_e32 v88, v129, v97
	v_cmp_le_u32_e64 s[6:7], v88, v104
	s_and_b64 s[6:7], vcc, s[6:7]
	v_add_u32_e32 v97, 1, v88
	v_cndmask_b32_e64 v80, v123, v80, s[6:7]
	v_cndmask_b32_e64 v68, v123, v68, s[6:7]
	v_cmp_le_u32_e64 s[6:7], v97, v104
	s_and_b64 s[6:7], vcc, s[6:7]
	v_add_u32_e32 v97, 2, v88
	v_cndmask_b32_e64 v81, v123, v81, s[6:7]
	v_cndmask_b32_e64 v69, v123, v69, s[6:7]
	v_cmp_le_u32_e64 s[6:7], v97, v104
	s_and_b64 s[6:7], vcc, s[6:7]
	v_add_u32_e32 v97, 3, v88
	v_cndmask_b32_e64 v82, v123, v82, s[6:7]
	v_cndmask_b32_e64 v70, v123, v70, s[6:7]
	v_cmp_le_u32_e64 s[6:7], v97, v104
	s_and_b64 s[6:7], vcc, s[6:7]
	v_add_u32_e32 v97, 16, v88
	v_cndmask_b32_e64 v83, v123, v83, s[6:7]
	v_cndmask_b32_e64 v71, v123, v71, s[6:7]
	v_cmp_le_u32_e64 s[6:7], v97, v104
	s_and_b64 s[6:7], vcc, s[6:7]
	v_add_u32_e32 v97, 17, v88
	v_cndmask_b32_e64 v72, v123, v72, s[6:7]
	v_cndmask_b32_e64 v64, v123, v64, s[6:7]
	v_cmp_le_u32_e64 s[6:7], v97, v104
	s_and_b64 s[6:7], vcc, s[6:7]
	v_add_u32_e32 v97, 18, v88
	v_cndmask_b32_e64 v73, v123, v73, s[6:7]
	v_cndmask_b32_e64 v65, v123, v65, s[6:7]
	v_cmp_le_u32_e64 s[6:7], v97, v104
	s_and_b64 s[6:7], vcc, s[6:7]
	v_add_u32_e32 v97, 19, v88
	v_cndmask_b32_e64 v74, v123, v74, s[6:7]
	v_cndmask_b32_e64 v66, v123, v66, s[6:7]
	v_cmp_le_u32_e64 s[6:7], v97, v104
	s_and_b64 s[6:7], vcc, s[6:7]
	v_add_u32_e32 v97, 32, v88
	v_cndmask_b32_e64 v75, v123, v75, s[6:7]
	v_cndmask_b32_e64 v67, v123, v67, s[6:7]
	v_cmp_le_u32_e64 s[6:7], v97, v104
	s_and_b64 s[6:7], vcc, s[6:7]
	v_add_u32_e32 v97, 33, v88
	v_cndmask_b32_e64 v84, v123, v84, s[6:7]
	v_cndmask_b32_e64 v60, v123, v60, s[6:7]
	v_cmp_le_u32_e64 s[6:7], v97, v104
	s_and_b64 s[6:7], vcc, s[6:7]
	v_add_u32_e32 v97, 34, v88
	v_cndmask_b32_e64 v85, v123, v85, s[6:7]
	v_cndmask_b32_e64 v61, v123, v61, s[6:7]
	v_cmp_le_u32_e64 s[6:7], v97, v104
	s_and_b64 s[6:7], vcc, s[6:7]
	v_add_u32_e32 v97, 35, v88
	v_cndmask_b32_e64 v86, v123, v86, s[6:7]
	v_cndmask_b32_e64 v62, v123, v62, s[6:7]
	v_cmp_le_u32_e64 s[6:7], v97, v104
	s_and_b64 s[6:7], vcc, s[6:7]
	v_add_u32_e32 v97, 48, v88
	v_cndmask_b32_e64 v87, v123, v87, s[6:7]
	v_cndmask_b32_e64 v63, v123, v63, s[6:7]
	v_cmp_le_u32_e64 s[6:7], v97, v104
	s_and_b64 s[6:7], vcc, s[6:7]
	v_add_u32_e32 v97, 49, v88
	v_cndmask_b32_e64 v76, v123, v76, s[6:7]
	v_cndmask_b32_e64 v56, v123, v56, s[6:7]
	v_cmp_le_u32_e64 s[6:7], v97, v104
	s_and_b64 s[6:7], vcc, s[6:7]
	v_add_u32_e32 v97, 50, v88
	v_cndmask_b32_e64 v77, v123, v77, s[6:7]
	v_cndmask_b32_e64 v57, v123, v57, s[6:7]
	v_cmp_le_u32_e64 s[6:7], v97, v104
	s_and_b64 s[6:7], vcc, s[6:7]
	v_add_u32_e32 v88, 51, v88
	v_cndmask_b32_e64 v78, v123, v78, s[6:7]
	v_cndmask_b32_e64 v58, v123, v58, s[6:7]
	v_cmp_le_u32_e64 s[6:7], v88, v104
	s_and_b64 vcc, vcc, s[6:7]
	v_cndmask_b32_e32 v79, v123, v79, vcc
	v_cndmask_b32_e32 v59, v123, v59, vcc
; __device__ __forceinline__ float exp2f_(float x) { return __builtin_amdgcn_exp2f(x); }
; __device__ __forceinline__ void nsa_block_step(const bf16_t* Ks, const bf16_t* VT, const bf16x8 (&qf)[2][2], f32x4 (&O)[2][4], float (&m)[2], float (&l)[2],
;                                                int klo, int khi, int r, int q) {
;     ...
;     bf16x8 pbv[2][2];
; #pragma unroll
;     for (int x = 0; x < 2; x++) {
;         float mx = fmaxf(fmaxf(fmaxf(s[x][0][0], s[x][0][1]), fmaxf(s[x][0][2], s[x][0][3])), fmaxf(fmaxf(s[x][1][0], s[x][1][1]), fmaxf(s[x][1][2], s[x][1][3])));
;         mx = fmaxf(mx, fmaxf(fmaxf(fmaxf(s[x][2][0], s[x][2][1]), fmaxf(s[x][2][2], s[x][2][3])), fmaxf(fmaxf(s[x][3][0], s[x][3][1]), fmaxf(s[x][3][2], s[x][3][3]))));
;         mx = xrow_max(mx);
;         const float mnew = fmaxf(m[x], mx);
;         const float alpha = exp2f_(m[x] - mnew);
;         m[x] = mnew;
;         float ls = 0.f;
; #pragma unroll
;         for (int kt = 0; kt < 4; kt++)
; #pragma unroll
;             for (int j = 0; j < 4; j++) { const float pv = exp2f_(s[x][kt][j] - mnew); s[x][kt][j] = pv; ls += pv; }
;         l[x] = l[x] * alpha + ls;
; #pragma unroll
;         for (int dt = 0; dt < 4; dt++) O[x][dt] *= alpha;
.LBB0_628:
	v_max3_f32 v88, v80, v81, v82
	v_max3_f32 v164, v68, v69, v70
	v_max3_f32 v97, v72, v73, v74
	v_max3_f32 v165, v64, v65, v66
	v_max3_f32 v104, v84, v85, v86
	v_max3_f32 v166, v60, v61, v62
	v_max3_f32 v105, v76, v77, v78
	v_max3_f32 v167, v56, v57, v58
	v_max3_f32 v88, v88, v83, v75
	v_max3_f32 v164, v164, v71, v67
	v_max3_f32 v97, v97, v87, v79
	v_max3_f32 v165, v165, v63, v59
	v_max3_f32 v88, v88, v97, v104
	v_max3_f32 v164, v164, v165, v166
	v_max_f32_e32 v88, v88, v105
	v_max_f32_e32 v164, v164, v167
	v_cmp_gt_f32_e32 vcc, v88, v178
	v_cmp_gt_f32_e64 s[46:47], v164, v179
	s_or_b64 vcc, vcc, s[46:47]
	s_cbranch_vccz .Ln2_fast
	v_add_f32_e32 v180, v103, v176
	v_add_f32_e32 v182, v102, v177
	v_mov_b32_e32 v97, v88
	v_mov_b32_e32 v165, v164
	s_nop 0
	v_permlane16_swap_b32_e32 v88, v97
	s_nop 0
	v_permlane16_swap_b32_e32 v164, v165
	v_max_f32_e32 v88, v88, v97
	v_max_f32_e32 v164, v164, v165
	v_mov_b32_e32 v97, v88
	v_mov_b32_e32 v165, v164
	s_nop 0
	v_permlane32_swap_b32_e32 v88, v97
	s_nop 0
	v_permlane32_swap_b32_e32 v164, v165
	v_max3_f32 v88, v180, v88, v97
	v_sub_f32_e32 v72, v72, v88
	v_exp_f32_e32 v105, v72
	v_sub_f32_e32 v72, v73, v88
	v_exp_f32_e32 v109, v72
	v_sub_f32_e32 v72, v74, v88
	v_exp_f32_e32 v107, v72
	v_sub_f32_e32 v72, v75, v88
	v_sub_f32_e32 v80, v80, v88
	v_exp_f32_e32 v111, v72
	v_sub_f32_e32 v72, v84, v88
	v_exp_f32_e32 v117, v80
	v_sub_f32_e32 v80, v81, v88
	v_exp_f32_e32 v73, v72
	v_sub_f32_e32 v72, v85, v88
	v_exp_f32_e32 v113, v80
	v_sub_f32_e32 v80, v82, v88
	v_exp_f32_e32 v75, v72
	v_sub_f32_e32 v72, v86, v88
	v_exp_f32_e32 v115, v80
	v_sub_f32_e32 v80, v83, v88
	v_exp_f32_e32 v83, v72
	v_sub_f32_e32 v72, v87, v88
	v_exp_f32_e32 v81, v72
	v_sub_f32_e32 v72, v76, v88
	v_exp_f32_e32 v85, v72
	v_sub_f32_e32 v72, v77, v88
	v_exp_f32_e32 v87, v72
	v_sub_f32_e32 v72, v78, v88
	v_exp_f32_e32 v77, v72
	v_sub_f32_e32 v72, v79, v88
	v_exp_f32_e32 v79, v72
	v_sub_f32_e32 v97, v180, v88
	v_exp_f32_e32 v103, v80
	v_exp_f32_e32 v76, v97
	v_max3_f32 v97, v182, v164, v165
	v_sub_f32_e32 v64, v64, v97
	v_sub_f32_e32 v68, v68, v97
	v_exp_f32_e32 v104, v64
	v_sub_f32_e32 v64, v65, v97
	v_sub_f32_e32 v78, v182, v97
	v_exp_f32_e32 v116, v68
	v_sub_f32_e32 v68, v69, v97
	v_exp_f32_e32 v108, v64
	v_sub_f32_e32 v64, v66, v97
	v_exp_f32_e32 v112, v68
	v_exp_f32_e32 v106, v64
	v_sub_f32_e32 v64, v67, v97
	v_sub_f32_e32 v60, v60, v97
	v_exp_f32_e32 v160, v78
	v_add_u32_e32 v78, 0x4800, v135
	v_exp_f32_e32 v110, v64
	v_exp_f32_e32 v72, v60
	v_sub_f32_e32 v60, v61, v97
	ds_read2_b64 v[64:67], v78 offset1:4
	v_exp_f32_e32 v74, v60
	v_sub_f32_e32 v60, v62, v97
	v_sub_f32_e32 v68, v70, v97
	v_exp_f32_e32 v82, v60
	v_sub_f32_e32 v60, v63, v97
	v_exp_f32_e32 v114, v68
	v_sub_f32_e32 v68, v71, v97
	v_pk_add_f32 v[156:157], v[116:117], 0 op_sel_hi:[1,0]
	v_exp_f32_e32 v80, v60
	v_cvt_pk_bf16_f32 v60, v116, v112
	v_add_u32_e32 v116, 0x5000, v135
	v_exp_f32_e32 v102, v68
	ds_read2_b64 v[68:71], v116 offset0:32 offset1:36
	v_mov_b32_e32 v161, v76
	v_pk_mul_f32 v[146:147], v[54:55], v[76:77] op_sel_hi:[1,0]
	v_pk_mul_f32 v[144:145], v[52:53], v[76:77] op_sel_hi:[1,0]
	v_cvt_pk_bf16_f32 v52, v117, v113
	v_cvt_pk_bf16_f32 v53, v115, v103
	v_cvt_pk_bf16_f32 v54, v105, v109
	v_cvt_pk_bf16_f32 v55, v107, v111
	v_pk_mul_f32 v[38:39], v[38:39], v[160:161] op_sel_hi:[1,0]
	v_pk_mul_f32 v[36:37], v[36:37], v[160:161] op_sel_hi:[1,0]
	v_cvt_pk_bf16_f32 v61, v114, v102
	v_cvt_pk_bf16_f32 v62, v104, v108
	v_cvt_pk_bf16_f32 v63, v106, v110
	v_add_u32_e32 v117, 0x5800, v135
	s_waitcnt lgkmcnt(1)
	v_mfma_f32_16x16x32_bf16 v[144:147], v[64:67], v[52:55], v[144:147]
	v_mul_f32_e64 v150, v50, v76
	v_mul_f32_e64 v151, v51, v76
	v_pk_mul_f32 v[148:149], v[48:49], v[76:77] op_sel_hi:[1,0]
	v_pk_mul_f32 v[34:35], v[34:35], v[160:161] op_sel_hi:[1,0]
	v_mfma_f32_16x16x32_bf16 v[36:39], v[64:67], v[60:63], v[36:39]
	ds_read2_b64 v[64:67], v117 offset0:64 offset1:68
	v_pk_mul_f32 v[32:33], v[32:33], v[160:161] op_sel_hi:[1,0]
	v_add_u32_e32 v162, 0x6000, v135
	s_waitcnt lgkmcnt(1)
	v_mfma_f32_16x16x32_bf16 v[148:151], v[68:71], v[52:55], v[148:151]
	v_mul_f32_e64 v50, v46, v76
	v_mul_f32_e64 v51, v47, v76
	v_pk_mul_f32 v[48:49], v[44:45], v[76:77] op_sel_hi:[1,0]
	v_pk_mul_f32 v[46:47], v[42:43], v[76:77] op_sel_hi:[1,0]
	v_mfma_f32_16x16x32_bf16 v[32:35], v[68:71], v[60:63], v[32:35]
	ds_read2_b64 v[68:71], v162 offset0:96 offset1:100
	v_pk_mul_f32 v[44:45], v[40:41], v[76:77] op_sel_hi:[1,0]
	v_sub_f32_e32 v56, v56, v97
	s_waitcnt lgkmcnt(1)
	v_mfma_f32_16x16x32_bf16 v[152:155], v[64:67], v[52:55], v[48:51]
	v_mul_f32_e64 v30, v30, v160
	v_mul_f32_e64 v31, v31, v160
	v_pk_mul_f32 v[28:29], v[28:29], v[160:161] op_sel_hi:[1,0]
	v_exp_f32_e32 v84, v56
	v_sub_f32_e32 v48, v58, v97
	v_exp_f32_e32 v76, v48
	ds_read2_b64 v[48:51], v78 offset0:8 offset1:12
	v_sub_f32_e32 v56, v57, v97
	v_mfma_f32_16x16x32_bf16 v[28:31], v[64:67], v[60:63], v[28:31]
	v_exp_f32_e32 v86, v56
	v_cvt_pk_bf16_f32 v40, v73, v75
	v_cvt_pk_bf16_f32 v41, v83, v81
	s_waitcnt lgkmcnt(1)
	v_mfma_f32_16x16x32_bf16 v[64:67], v[68:71], v[52:55], v[44:47]
	v_cvt_pk_bf16_f32 v42, v85, v87
	v_cvt_pk_bf16_f32 v43, v77, v79
	v_cvt_pk_bf16_f32 v56, v72, v74
	v_sub_f32_e32 v44, v59, v97
	v_exp_f32_e32 v78, v44
	ds_read2_b64 v[44:47], v116 offset0:40 offset1:44
	v_cvt_pk_bf16_f32 v57, v82, v80
	v_cvt_pk_bf16_f32 v58, v84, v86
	v_cvt_pk_bf16_f32 v59, v76, v78
	v_pk_mul_f32 v[26:27], v[26:27], v[160:161] op_sel_hi:[1,0]
	v_pk_mul_f32 v[24:25], v[24:25], v[160:161] op_sel_hi:[1,0]
	s_waitcnt lgkmcnt(1)
; __device__ __forceinline__ float sigmoidf_(float x) { return __builtin_amdgcn_rcpf(1.f + __expf(-x)); }
; __device__ __forceinline__ f32x4 mfma16(bf16x8 a, bf16x8 b, f32x4 c) { return __builtin_amdgcn_mfma_f32_16x16x32_bf16(a, b, c, 0, 0, 0); }
; __device__ __forceinline__ void nsa_block_step(const bf16_t* Ks, const bf16_t* VT, const bf16x8 (&qf)[2][2], f32x4 (&O)[2][4], float (&m)[2], float (&l)[2],
;                                                int klo, int khi, int r, int q) {
;     ...
;         l[x] = l[x] * alpha + ls;
; #pragma unroll
;         for (int dt = 0; dt < 4; dt++) O[x][dt] *= alpha;
; #pragma unroll
;         for (int s2 = 0; s2 < 2; s2++) {
;             const u32x4 t4 = {pack2(s[x][2 * s2][0], s[x][2 * s2][1]), pack2(s[x][2 * s2][2], s[x][2 * s2][3]),
;                               pack2(s[x][2 * s2 + 1][0], s[x][2 * s2 + 1][1]), pack2(s[x][2 * s2 + 1][2], s[x][2 * s2 + 1][3])};
;             pbv[x][s2] = __builtin_bit_cast(bf16x8, t4);
;         }
;     }
; #pragma unroll
;     for (int s2 = 0; s2 < 2; s2++)
; #pragma unroll
;         for (int dt = 0; dt < 4; dt++) {
;             const u32x2 lo = *(const u32x2*)(VT + (dt * 16 + r) * 72 + (2 * s2) * 16 + 4 * q);
;             const u32x2 hi = *(const u32x2*)(VT + (dt * 16 + r) * 72 + (2 * s2 + 1) * 16 + 4 * q);
;             const bf16x8 va = mk_frag(lo, hi);
; #pragma unroll
;             for (int x = 0; x < 2; x++) O[x][dt] = mfma16(va, pbv[x][s2], O[x][dt]);
;         }
; __device__ void phaseN2_task(const Params& p, int task, char* lds, bf16_t* ydst, int ystride, volatile unsigned* uex, char* ldsb) {
;     ...
;             if (nbr != br) {
; #pragma unroll
;                 for (int x = 0; x < 2; x++) {
;                     float lt = l[x];
;                     lt = xrow_sum(lt);
;                     const float sc = sigmoidf_(br == 0 ? gatev[1][x] : gatev[2][x]) / lt;
; #pragma unroll
;                     for (int dt = 0; dt < 4; dt++) { ofl[(wave * 8 + x * 4 + dt) * 64 + lane] += sc * O[x][dt]; O[x][dt] = (f32x4){0.f, 0.f, 0.f, 0.f}; }
;                     m[x] = -1e30f; l[x] = 0.f;
;                 }
;             }
	v_mfma_f32_16x16x32_bf16 v[52:55], v[48:51], v[40:43], v[144:147]
	v_cmp_ne_u32_e32 vcc, v141, v143
	v_mfma_f32_16x16x32_bf16 v[36:39], v[48:51], v[56:59], v[36:39]
	v_add_f32_e64 v48, v112, v156
	v_add_f32_e64 v49, v113, v157
	v_mfma_f32_16x16x32_bf16 v[24:27], v[68:71], v[60:63], v[24:27]
	v_add_f32_e64 v68, v114, v48
	v_add_f32_e64 v69, v115, v49
	ds_read2_b64 v[60:63], v117 offset0:72 offset1:76
	v_pk_add_f32 v[68:69], v[102:103], v[68:69]
	s_waitcnt lgkmcnt(1)
	v_mfma_f32_16x16x32_bf16 v[48:51], v[44:47], v[40:43], v[148:151]
	v_add_f32_e64 v68, v104, v68
	v_add_f32_e64 v69, v105, v69
	v_pk_add_f32 v[68:69], v[108:109], v[68:69]
	v_mfma_f32_16x16x32_bf16 v[32:35], v[44:47], v[56:59], v[32:35]
	v_add_f32_e64 v44, v106, v68
	v_add_f32_e64 v45, v107, v69
	ds_read2_b64 v[68:71], v162 offset0:104 offset1:108
	v_pk_add_f32 v[102:103], v[110:111], v[44:45]
	s_waitcnt lgkmcnt(1)
	v_mfma_f32_16x16x32_bf16 v[44:47], v[60:63], v[40:43], v[152:155]
	v_add_f32_e64 v72, v72, v102
	v_add_f32_e64 v73, v73, v103
	v_pk_add_f32 v[72:73], v[74:75], v[72:73]
	v_mfma_f32_16x16x32_bf16 v[28:31], v[60:63], v[56:59], v[28:31]
	v_add_f32_e64 v72, v82, v72
	v_add_f32_e64 v73, v83, v73
	v_pk_add_f32 v[60:61], v[80:81], v[72:73]
	s_waitcnt lgkmcnt(0)
	v_mfma_f32_16x16x32_bf16 v[40:43], v[68:71], v[40:43], v[64:67]
	v_add_f32_e64 v60, v84, v60
	v_add_f32_e64 v61, v85, v61
	v_pk_add_f32 v[60:61], v[86:87], v[60:61]
	v_mfma_f32_16x16x32_bf16 v[24:27], v[68:71], v[56:59], v[24:27]
	v_add_f32_e64 v60, v76, v60
	v_add_f32_e64 v61, v77, v61
	v_pk_add_f32 v[60:61], v[78:79], v[60:61]
	s_nop 0
	v_pk_fma_f32 v[100:101], v[100:101], v[160:161], v[60:61]
	s_mov_b32 s45, 0xf0a18f08
	v_sub_f32_e32 v88, v88, v176
	v_sub_f32_e32 v97, v97, v177
	v_cmp_lt_f32_e64 s[46:47], v88, s45
	v_cmp_lt_f32_e64 s[48:49], v97, s45
	v_sub_f32_e32 v176, 0, v88
	v_sub_f32_e32 v177, 0, v97
	v_cndmask_b32_e64 v176, v176, 0, s[46:47]
	v_cndmask_b32_e64 v177, v177, 0, s[48:49]
	v_cndmask_b32_e64 v178, 4.0, v123, s[46:47]
	v_cndmask_b32_e64 v179, 4.0, v123, s[48:49]
.Ln2_tail:
	s_and_saveexec_b64 s[6:7], vcc
	s_cbranch_execz .LBB0_617
	s_mov_b64 vcc, s[4:5]
	v_cndmask_b32_sdwa v57, v128, v127, vcc dst_sel:WORD_1 dst_unused:UNUSED_PAD src0_sel:DWORD src1_sel:DWORD
	v_mov_b32_e32 v56, v101
	v_mul_f32_e32 v57, 0xbfb8aa3b, v57
	v_exp_f32_e32 v57, v57
	v_permlane16_swap_b32_e32 v101, v56
	v_add_f32_e32 v56, v101, v56
	v_add_f32_e32 v57, 1.0, v57
	v_rcp_f32_e32 v60, v57
	v_mov_b32_e32 v58, v56
	s_nop 1
	v_permlane32_swap_b32_e32 v56, v58
	v_add_f32_e32 v61, v56, v58
	v_div_scale_f32 v56, s[10:11], v61, v61, v60
	v_rcp_f32_e32 v62, v56
	v_mov_b32_e32 v97, 0xf149f2ca
	v_mov_b32_e32 v88, 0xf149f2ca
	v_mov_b32_e32 v176, 0
	v_mov_b32_e32 v177, 0
	v_mov_b32_e32 v178, v123
	v_mov_b32_e32 v179, v123
	v_fma_f32 v57, -v56, v62, 1.0
	v_fmac_f32_e32 v62, v57, v62
	v_div_scale_f32 v57, vcc, v60, v61, v60
	v_mul_f32_e32 v63, v57, v62
	v_fma_f32 v58, -v56, v63, v57
	v_fmac_f32_e32 v63, v58, v62
	v_fma_f32 v64, -v56, v63, v57
	ds_read_b128 v[56:59], v131 offset:35840
	v_div_fmas_f32 v62, v64, v62, v63
	v_div_fixup_f32 v64, v62, v61, v60
	ds_read_b128 v[60:63], v131 offset:36864
	s_waitcnt lgkmcnt(1)
	v_pk_fma_f32 v[54:55], v[54:55], v[64:65], v[58:59] op_sel_hi:[1,0,1]
	v_pk_fma_f32 v[52:53], v[52:53], v[64:65], v[56:57] op_sel_hi:[1,0,1]
	ds_write_b128 v131, v[52:55] offset:35840
	ds_read_b128 v[52:55], v131 offset:37888
	s_waitcnt lgkmcnt(2)
	v_pk_fma_f32 v[50:51], v[50:51], v[64:65], v[62:63] op_sel_hi:[1,0,1]
	v_pk_fma_f32 v[48:49], v[48:49], v[64:65], v[60:61] op_sel_hi:[1,0,1]
	ds_write_b128 v131, v[48:51] offset:36864
	ds_read_b128 v[48:51], v131 offset:38912
	s_waitcnt lgkmcnt(2)
	v_pk_fma_f32 v[46:47], v[46:47], v[64:65], v[54:55] op_sel_hi:[1,0,1]
	v_pk_fma_f32 v[44:45], v[44:45], v[64:65], v[52:53] op_sel_hi:[1,0,1]
	ds_write_b128 v131, v[44:47] offset:37888
	v_cndmask_b32_e64 v45, v133, v93, s[4:5]
	v_lshlrev_b32_e32 v45, 16, v45
	v_mul_f32_e32 v45, 0xbfb8aa3b, v45
	v_exp_f32_e32 v45, v45
	v_mov_b32_e32 v44, v100
	s_nop 1
	v_permlane16_swap_b32_e32 v100, v44
	v_add_f32_e32 v45, 1.0, v45
	v_add_f32_e32 v44, v100, v44
	v_rcp_f32_e32 v45, v45
	v_mov_b32_e32 v46, v44
	s_nop 1
	v_permlane32_swap_b32_e32 v44, v46
	v_add_f32_e32 v44, v44, v46
	v_div_scale_f32 v46, s[4:5], v44, v44, v45
	v_rcp_f32_e32 v47, v46
	s_waitcnt lgkmcnt(1)
	v_pk_fma_f32 v[42:43], v[42:43], v[64:65], v[50:51] op_sel_hi:[1,0,1]
	v_pk_fma_f32 v[40:41], v[40:41], v[64:65], v[48:49] op_sel_hi:[1,0,1]
	ds_write_b128 v131, v[40:43] offset:38912
	v_fma_f32 v40, -v46, v47, 1.0
	v_fmac_f32_e32 v47, v40, v47
	v_div_scale_f32 v40, vcc, v45, v44, v45
	v_mul_f32_e32 v48, v40, v47
	v_fma_f32 v41, -v46, v48, v40
	v_fmac_f32_e32 v48, v41, v47
	v_fma_f32 v46, -v46, v48, v40
	ds_read_b128 v[40:43], v131 offset:39936
	v_div_fmas_f32 v46, v46, v47, v48
	v_div_fixup_f32 v48, v46, v44, v45
	ds_read_b128 v[44:47], v131 offset:40960
	s_waitcnt lgkmcnt(1)
	v_pk_fma_f32 v[38:39], v[38:39], v[48:49], v[42:43] op_sel_hi:[1,0,1]
	v_pk_fma_f32 v[36:37], v[36:37], v[48:49], v[40:41] op_sel_hi:[1,0,1]
	ds_write_b128 v131, v[36:39] offset:39936
	ds_read_b128 v[36:39], v131 offset:41984
	ds_read_b128 v[40:43], v131 offset:43008
	s_waitcnt lgkmcnt(3)
	v_pk_fma_f32 v[34:35], v[34:35], v[48:49], v[46:47] op_sel_hi:[1,0,1]
	v_pk_fma_f32 v[32:33], v[32:33], v[48:49], v[44:45] op_sel_hi:[1,0,1]
	ds_write_b128 v131, v[32:35] offset:40960
	s_waitcnt lgkmcnt(2)
	v_pk_fma_f32 v[30:31], v[30:31], v[48:49], v[38:39] op_sel_hi:[1,0,1]
	s_waitcnt lgkmcnt(1)
	v_pk_fma_f32 v[26:27], v[26:27], v[48:49], v[42:43] op_sel_hi:[1,0,1]
	v_pk_fma_f32 v[24:25], v[24:25], v[48:49], v[40:41] op_sel_hi:[1,0,1]
	v_pk_fma_f32 v[28:29], v[28:29], v[48:49], v[36:37] op_sel_hi:[1,0,1]
	ds_write_b128 v131, v[24:27] offset:43008
	v_mov_b32_e32 v24, 0
	ds_write_b128 v131, v[28:31] offset:41984
	v_mov_b32_e32 v25, v24
	v_mov_b32_e32 v26, v24
	v_mov_b32_e32 v27, v24
	v_mov_b32_e32 v28, v24
	v_mov_b32_e32 v29, v24
	v_mov_b32_e32 v30, v24
	v_mov_b32_e32 v31, v24
	v_mov_b32_e32 v32, v24
	v_mov_b32_e32 v33, v24
	v_mov_b32_e32 v34, v24
	v_mov_b32_e32 v35, v24
	v_mov_b32_e32 v36, v24
	v_mov_b32_e32 v37, v24
	v_mov_b32_e32 v38, v24
	v_mov_b32_e32 v39, v24
	v_mov_b32_e32 v40, v24
	v_mov_b32_e32 v41, v24
	v_mov_b32_e32 v42, v24
	v_mov_b32_e32 v43, v24
	v_mov_b32_e32 v44, v24
	v_mov_b32_e32 v45, v24
	v_mov_b32_e32 v46, v24
	v_mov_b32_e32 v47, v24
	v_mov_b32_e32 v48, v24
	v_mov_b32_e32 v49, v24
	v_mov_b32_e32 v50, v24
	v_mov_b32_e32 v51, v24
	v_mov_b32_e32 v52, v24
	v_mov_b32_e32 v53, v24
	v_mov_b32_e32 v54, v24
	v_mov_b32_e32 v55, v24
	v_mov_b32_e32 v100, v24
	v_mov_b32_e32 v101, v24
	s_branch .LBB0_617
; __device__ __forceinline__ float exp2f_(float x) { return __builtin_amdgcn_exp2f(x); }
; __device__ __forceinline__ f32x4 mfma16(bf16x8 a, bf16x8 b, f32x4 c) { return __builtin_amdgcn_mfma_f32_16x16x32_bf16(a, b, c, 0, 0, 0); }
; __device__ __forceinline__ void nsa_block_step(const bf16_t* Ks, const bf16_t* VT, const bf16x8 (&qf)[2][2], f32x4 (&O)[2][4], float (&m)[2], float (&l)[2],
;                                                int klo, int khi, int r, int q) {
;     ...
;     bf16x8 pbv[2][2];
; #pragma unroll
;     for (int x = 0; x < 2; x++) {
;         float mx = fmaxf(fmaxf(fmaxf(s[x][0][0], s[x][0][1]), fmaxf(s[x][0][2], s[x][0][3])), fmaxf(fmaxf(s[x][1][0], s[x][1][1]), fmaxf(s[x][1][2], s[x][1][3])));
;         mx = fmaxf(mx, fmaxf(fmaxf(fmaxf(s[x][2][0], s[x][2][1]), fmaxf(s[x][2][2], s[x][2][3])), fmaxf(fmaxf(s[x][3][0], s[x][3][1]), fmaxf(s[x][3][2], s[x][3][3]))));
;         mx = xrow_max(mx);
;         const float mnew = fmaxf(m[x], mx);
;         const float alpha = exp2f_(m[x] - mnew);
;         m[x] = mnew;
;         float ls = 0.f;
; #pragma unroll
;         for (int kt = 0; kt < 4; kt++)
; #pragma unroll
;             for (int j = 0; j < 4; j++) { const float pv = exp2f_(s[x][kt][j] - mnew); s[x][kt][j] = pv; ls += pv; }
;         l[x] = l[x] * alpha + ls;
; #pragma unroll
;         for (int dt = 0; dt < 4; dt++) O[x][dt] *= alpha;
; #pragma unroll
;         for (int s2 = 0; s2 < 2; s2++) {
;             const u32x4 t4 = {pack2(s[x][2 * s2][0], s[x][2 * s2][1]), pack2(s[x][2 * s2][2], s[x][2 * s2][3]),
;                               pack2(s[x][2 * s2 + 1][0], s[x][2 * s2 + 1][1]), pack2(s[x][2 * s2 + 1][2], s[x][2 * s2 + 1][3])};
;             pbv[x][s2] = __builtin_bit_cast(bf16x8, t4);
;         }
;     }
; #pragma unroll
;     for (int s2 = 0; s2 < 2; s2++)
; #pragma unroll
;         for (int dt = 0; dt < 4; dt++) {
;             const u32x2 lo = *(const u32x2*)(VT + (dt * 16 + r) * 72 + (2 * s2) * 16 + 4 * q);
;             const u32x2 hi = *(const u32x2*)(VT + (dt * 16 + r) * 72 + (2 * s2 + 1) * 16 + 4 * q);
;             const bf16x8 va = mk_frag(lo, hi);
; #pragma unroll
;             for (int x = 0; x < 2; x++) O[x][dt] = mfma16(va, pbv[x][s2], O[x][dt]);
;         }
.Ln2_fast:
	v_add_u32_e32 v216, 0x4800, v135
	v_add_u32_e32 v217, 0x5000, v135
	v_add_u32_e32 v218, 0x5800, v135
	v_add_u32_e32 v219, 0x6000, v135
	ds_read2_b64 v[200:203], v216 offset1:4
	ds_read2_b64 v[204:207], v217 offset0:32 offset1:36
	ds_read2_b64 v[208:211], v218 offset0:64 offset1:68
	ds_read2_b64 v[212:215], v219 offset0:96 offset1:100
	v_exp_f32_e32 v80, v80
	v_exp_f32_e32 v81, v81
	v_exp_f32_e32 v82, v82
	v_exp_f32_e32 v83, v83
	v_exp_f32_e32 v72, v72
	v_exp_f32_e32 v73, v73
	v_exp_f32_e32 v74, v74
	v_exp_f32_e32 v75, v75
	ds_read2_b64 v[224:227], v216 offset0:8 offset1:12
	ds_read2_b64 v[228:231], v217 offset0:40 offset1:44
	v_exp_f32_e32 v68, v68
	v_exp_f32_e32 v69, v69
	v_exp_f32_e32 v70, v70
	v_exp_f32_e32 v71, v71
	v_exp_f32_e32 v64, v64
	v_exp_f32_e32 v65, v65
	v_exp_f32_e32 v66, v66
	v_exp_f32_e32 v67, v67
	ds_read2_b64 v[232:235], v218 offset0:72 offset1:76
	ds_read2_b64 v[236:239], v219 offset0:104 offset1:108
	v_cvt_pk_bf16_f32 v184, v80, v81
	v_cvt_pk_bf16_f32 v185, v82, v83
	v_cvt_pk_bf16_f32 v186, v72, v73
	v_cvt_pk_bf16_f32 v187, v74, v75
	v_cvt_pk_bf16_f32 v192, v68, v69
	v_cvt_pk_bf16_f32 v193, v70, v71
	v_cvt_pk_bf16_f32 v194, v64, v65
	v_cvt_pk_bf16_f32 v195, v66, v67
	v_exp_f32_e32 v84, v84
	v_exp_f32_e32 v85, v85
	s_waitcnt lgkmcnt(7)
	v_mfma_f32_16x16x32_bf16 v[52:55], v[200:203], v[184:187], v[52:55]
	v_exp_f32_e32 v86, v86
	v_exp_f32_e32 v87, v87
	v_mfma_f32_16x16x32_bf16 v[36:39], v[200:203], v[192:195], v[36:39]
	v_exp_f32_e32 v76, v76
	v_exp_f32_e32 v77, v77
	s_waitcnt lgkmcnt(6)
	v_mfma_f32_16x16x32_bf16 v[48:51], v[204:207], v[184:187], v[48:51]
	v_exp_f32_e32 v78, v78
	v_exp_f32_e32 v79, v79
	v_mfma_f32_16x16x32_bf16 v[32:35], v[204:207], v[192:195], v[32:35]
	v_exp_f32_e32 v60, v60
	v_exp_f32_e32 v61, v61
	s_waitcnt lgkmcnt(5)
	v_mfma_f32_16x16x32_bf16 v[44:47], v[208:211], v[184:187], v[44:47]
	v_exp_f32_e32 v62, v62
	v_exp_f32_e32 v63, v63
	v_mfma_f32_16x16x32_bf16 v[28:31], v[208:211], v[192:195], v[28:31]
	v_exp_f32_e32 v56, v56
	v_exp_f32_e32 v57, v57
	s_waitcnt lgkmcnt(4)
	v_mfma_f32_16x16x32_bf16 v[40:43], v[212:215], v[184:187], v[40:43]
	v_exp_f32_e32 v58, v58
	v_exp_f32_e32 v59, v59
	v_mfma_f32_16x16x32_bf16 v[24:27], v[212:215], v[192:195], v[24:27]
	v_cvt_pk_bf16_f32 v188, v84, v85
	v_cvt_pk_bf16_f32 v189, v86, v87
	v_cvt_pk_bf16_f32 v190, v76, v77
	v_cvt_pk_bf16_f32 v191, v78, v79
	v_cvt_pk_bf16_f32 v196, v60, v61
	v_cvt_pk_bf16_f32 v197, v62, v63
	v_cvt_pk_bf16_f32 v198, v56, v57
	v_cvt_pk_bf16_f32 v199, v58, v59
	v_add_f32_e32 v221, v80, v81
	v_add_f32_e32 v220, v68, v69
	s_waitcnt lgkmcnt(3)
	v_mfma_f32_16x16x32_bf16 v[52:55], v[224:227], v[188:191], v[52:55]
	v_add_f32_e32 v221, v221, v82
	v_add_f32_e32 v220, v220, v70
	v_mfma_f32_16x16x32_bf16 v[36:39], v[224:227], v[196:199], v[36:39]
	v_add_f32_e32 v221, v221, v83
	v_add_f32_e32 v220, v220, v71
	s_waitcnt lgkmcnt(2)
	v_mfma_f32_16x16x32_bf16 v[48:51], v[228:231], v[188:191], v[48:51]
	v_add_f32_e32 v221, v221, v72
	v_add_f32_e32 v220, v220, v64
	v_mfma_f32_16x16x32_bf16 v[32:35], v[228:231], v[196:199], v[32:35]
	v_add_f32_e32 v221, v221, v73
	v_add_f32_e32 v220, v220, v65
	s_waitcnt lgkmcnt(1)
	v_mfma_f32_16x16x32_bf16 v[44:47], v[232:235], v[188:191], v[44:47]
	v_add_f32_e32 v221, v221, v74
	v_add_f32_e32 v220, v220, v66
	v_mfma_f32_16x16x32_bf16 v[28:31], v[232:235], v[196:199], v[28:31]
	v_add_f32_e32 v221, v221, v75
	v_add_f32_e32 v220, v220, v67
	s_waitcnt lgkmcnt(0)
	v_mfma_f32_16x16x32_bf16 v[40:43], v[236:239], v[188:191], v[40:43]
	v_add_f32_e32 v221, v221, v84
	v_add_f32_e32 v220, v220, v60
	v_mfma_f32_16x16x32_bf16 v[24:27], v[236:239], v[196:199], v[24:27]
	v_add_f32_e32 v221, v221, v85
	v_add_f32_e32 v220, v220, v61
	v_add_f32_e32 v221, v221, v86
	v_add_f32_e32 v220, v220, v62
	v_add_f32_e32 v221, v221, v87
	v_add_f32_e32 v220, v220, v63
	v_add_f32_e32 v221, v221, v76
	v_add_f32_e32 v220, v220, v56
	v_add_f32_e32 v221, v221, v77
	v_add_f32_e32 v220, v220, v57
	v_add_f32_e32 v221, v221, v78
	v_add_f32_e32 v220, v220, v58
	v_add_f32_e32 v221, v221, v79
	v_add_f32_e32 v220, v220, v59
	v_cmp_ne_u32_e32 vcc, v141, v143
	v_mov_b32_e32 v88, v103
	v_mov_b32_e32 v97, v102
	v_pk_add_f32 v[100:101], v[100:101], v[220:221]
	s_branch .Ln2_tail

; __global__ void __launch_bounds__(BLOCK_THREADS, 2) mega(Params p_unused) {
;     __shared__ __attribute__((aligned(16))) char lds[LDS_BYTES];
	.amdhsa_kernel _Z4mega6Params
		.amdhsa_group_segment_fixed_size 147520
		.amdhsa_private_segment_fixed_size 0
		.amdhsa_kernarg_size 480
		.amdhsa_user_sgpr_count 2
		.amdhsa_user_sgpr_dispatch_ptr 0
		.amdhsa_user_sgpr_queue_ptr 0
		.amdhsa_user_sgpr_kernarg_segment_ptr 1
		.amdhsa_user_sgpr_dispatch_id 0
		.amdhsa_user_sgpr_kernarg_preload_length 0
		.amdhsa_user_sgpr_kernarg_preload_offset 0
		.amdhsa_user_sgpr_private_segment_size 0
		.amdhsa_uses_dynamic_stack 0
		.amdhsa_enable_private_segment 0
		.amdhsa_system_sgpr_workgroup_id_x 1
		.amdhsa_system_sgpr_workgroup_id_y 0
		.amdhsa_system_sgpr_workgroup_id_z 0
		.amdhsa_system_sgpr_workgroup_info 0
		.amdhsa_system_vgpr_workitem_id 2
		.amdhsa_next_free_vgpr 256
		.amdhsa_next_free_sgpr 98
		.amdhsa_accum_offset 256
		.amdhsa_reserve_vcc 1
		.amdhsa_float_round_mode_32 0
		.amdhsa_float_round_mode_16_64 0
		.amdhsa_float_denorm_mode_32 3
		.amdhsa_float_denorm_mode_16_64 3
		.amdhsa_dx10_clamp 1
		.amdhsa_ieee_mode 1
		.amdhsa_fp16_overflow 0
		.amdhsa_tg_split 0
		.amdhsa_exception_fp_ieee_invalid_op 0
		.amdhsa_exception_fp_denorm_src 0
		.amdhsa_exception_fp_ieee_div_zero 0
		.amdhsa_exception_fp_ieee_overflow 0
		.amdhsa_exception_fp_ieee_underflow 0
		.amdhsa_exception_fp_ieee_inexact 0
		.amdhsa_exception_int_div_zero 0
	.end_amdhsa_kernel

; __global__ void __launch_bounds__(BLOCK_THREADS, 2) mega(Params p_unused) {
;     __shared__ __attribute__((aligned(16))) char lds[LDS_BYTES];
amdhsa.kernels:
  - .agpr_count:     0
    .args:
      - .offset:         0
        .size:           224
        .value_kind:     by_value
      - .offset:         224
        .size:           4
        .value_kind:     hidden_block_count_x
      - .offset:         228
        .size:           4
        .value_kind:     hidden_block_count_y
      - .offset:         232
        .size:           4
        .value_kind:     hidden_block_count_z
      - .offset:         236
        .size:           2
        .value_kind:     hidden_group_size_x
      - .offset:         238
        .size:           2
        .value_kind:     hidden_group_size_y
      - .offset:         240
        .size:           2
        .value_kind:     hidden_group_size_z
      - .offset:         242
        .size:           2
        .value_kind:     hidden_remainder_x
      - .offset:         244
        .size:           2
        .value_kind:     hidden_remainder_y
      - .offset:         246
        .size:           2
        .value_kind:     hidden_remainder_z
      - .offset:         264
        .size:           8
        .value_kind:     hidden_global_offset_x
      - .offset:         272
        .size:           8
        .value_kind:     hidden_global_offset_y
      - .offset:         280
        .size:           8
        .value_kind:     hidden_global_offset_z
      - .offset:         288
        .size:           2
        .value_kind:     hidden_grid_dims
      - .offset:         312
        .size:           8
        .value_kind:     hidden_multigrid_sync_arg
    .group_segment_fixed_size: 147520
    .kernarg_segment_align: 8
    .kernarg_segment_size: 480
    .language:       OpenCL C
    .language_version:
      - 2
      - 0
    .max_flat_workgroup_size: 512
    .name:           _Z4mega6Params
    .private_segment_fixed_size: 0
    .sgpr_count:     104
    .sgpr_spill_count: 19
    .symbol:         _Z4mega6Params.kd
    .uniform_work_group_size: 1
    .uses_dynamic_stack: false
    .vgpr_count:     256
    .vgpr_spill_count: 0
    .wavefront_size: 64
